# setprio reorder + CONV_KT 32: all non-ff1 weight conversion moved into the idle CUs of the in-projection GEMM's last round
# baseline (speedup 1.0000x reference)
.LBB8_256:
	s_cmp_lt_i32 s92, 3
	s_mul_i32 s59, s59, s68
	s_cselect_b64 s[6:7], -1, 0
	s_sub_i32 s8, s58, s59
	s_sub_i32 s9, s8, s68
	s_cmp_ge_u32 s8, s68
	s_cselect_b32 s8, s9, s8
	s_sub_i32 s9, s8, s68
	s_cmp_ge_u32 s8, s68
	s_cselect_b32 s8, s9, s8
	s_xor_b32 s38, s8, s56
	s_sub_i32 s39, s38, s56
	s_mul_i32 s8, s39, 0x100
	s_and_b32 s8, s8, 0xffffff00
	s_cmpk_lt_i32 s39, 0x60
	v_readlane_b32 s10, v254, 2
	s_cselect_b32 s67, s8, 0x6000
	v_readlane_b32 s11, v254, 3
	s_add_u32 s68, s10, 0x200000
	s_addc_u32 s69, s11, 0
	s_add_u32 s54, s10, 0x800000
	s_addc_u32 s55, s11, 0
	s_add_u32 s36, s10, 0xc800000
	s_addc_u32 s37, s11, 0
	s_add_u32 s90, s10, 0x2a000000
	s_addc_u32 s91, s11, 0
	s_add_u32 s8, s10, 0x2b000000
	s_addc_u32 s9, s11, 0
	v_writelane_b32 v254, s8, 41
	s_nop 1
	v_writelane_b32 v254, s9, 42
	s_add_u32 s8, s10, 0x2c000000
	s_addc_u32 s9, s11, 0
	v_writelane_b32 v254, s8, 43
	s_nop 1
	v_writelane_b32 v254, s9, 44
	s_add_u32 s8, s10, 0x2e000000
	s_addc_u32 s9, s11, 0
	v_writelane_b32 v254, s8, 45
	s_add_u32 s88, s10, 0x36000000
	s_addc_u32 s89, s11, 0
	v_writelane_b32 v254, s9, 46
	s_and_b64 s[34:35], s[6:7], s[0:1]
	s_mov_b64 s[0:1], s[92:93]
	v_writelane_b32 v254, s0, 47
	s_andn2_b64 vcc, exec, s[34:35]
	s_nop 0
	v_writelane_b32 v254, s1, 48
	v_writelane_b32 v254, s2, 49
	v_writelane_b32 v254, s3, 50
	v_writelane_b32 v254, s68, 51
	s_nop 1
	v_writelane_b32 v254, s69, 52
	s_cbranch_vccnz .LBB8_357
	v_readlane_b32 s0, v254, 40
	s_waitcnt vmcnt(13) lgkmcnt(2)
	v_mbcnt_lo_u32_b32 v10, -1, 0
	v_mbcnt_hi_u32_b32 v10, -1, v10
	s_cmpk_gt_i32 s2, 0x99f
	s_waitcnt lgkmcnt(0)
	v_add_u32_e32 v0, s0, v10
	s_nop 0
	v_readfirstlane_b32 s1, v0
	s_cbranch_scc1 .LBB8_279
	v_lshlrev_b32_e32 v1, 4, v0
	v_add_u32_e32 v2, 0x2000, v1
	v_ashrrev_i32_e32 v3, 31, v2
	v_lshrrev_b32_e32 v3, 22, v3
	v_add_u32_e32 v3, v2, v3
	v_ashrrev_i32_e32 v8, 10, v3
	v_mul_i32_i24_e32 v3, 0x400, v8
	v_sub_u32_e32 v2, v2, v3
	v_lshrrev_b32_e32 v3, 4, v2
	v_bitop3_b32 v2, v3, v2, 32 bitop3:0x6c
	v_ashrrev_i32_e32 v3, 31, v2
	v_lshrrev_b32_e32 v3, 26, v3
	v_add_u32_e32 v3, v2, v3
	v_lshlrev_b32_e32 v4, 3, v8
	v_ashrrev_i32_e32 v9, 6, v3
	v_and_b32_e32 v4, -16, v4
	v_add_u32_e32 v4, v9, v4
	v_and_b32_e32 v5, 3, v9
	s_mov_b32 s0, 0x7ffe0
	v_lshrrev_b32_e32 v6, 2, v4
	v_lshlrev_b32_e32 v7, 1, v4
	v_and_b32_e32 v3, 0xc0, v3
	v_and_or_b32 v5, v4, s0, v5
	v_and_b32_e32 v6, 4, v6
	v_and_b32_e32 v7, 24, v7
	v_sub_u32_e32 v2, v2, v3
	v_mov_b32_e32 v3, 1
	v_or3_b32 v5, v5, v6, v7
	v_lshlrev_b32_e32 v6, 5, v8
	v_ashrrev_i16_sdwa v2, v3, sext(v2) dst_sel:DWORD dst_unused:UNUSED_PAD src0_sel:DWORD src1_sel:BYTE_0
	v_and_b32_e32 v6, 32, v6
	v_bfe_i32 v11, v2, 0, 16
	v_add_lshl_u32 v2, v6, v11, 1
	v_lshl_add_u32 v128, v5, 13, v2
	v_lshl_add_u32 v130, v4, 13, v2
	v_bfe_i32 v2, v0, 27, 1
	v_lshrrev_b32_e32 v2, 22, v2
	v_add_u32_e32 v2, v1, v2
	v_and_b32_e32 v2, 0xfffffc00, v2
	v_sub_u32_e32 v1, v1, v2
	v_lshrrev_b32_e32 v2, 4, v1
	v_ashrrev_i32_e32 v4, 31, v0
	v_bitop3_b32 v1, v2, v1, 32 bitop3:0x6c
	v_lshrrev_b32_e32 v4, 26, v4
	v_ashrrev_i32_e32 v2, 31, v1
	v_add_u32_e32 v0, v0, v4
	v_lshrrev_b32_e32 v2, 26, v2
	s_waitcnt vmcnt(12)
	v_ashrrev_i32_e32 v13, 6, v0
	v_add_u32_e32 v2, v1, v2
	v_lshlrev_b32_e32 v0, 3, v13
	v_ashrrev_i32_e32 v12, 6, v2
	v_and_b32_e32 v0, -16, v0
	v_add_u32_e32 v0, v12, v0
	v_and_b32_e32 v4, 3, v12
	s_ashr_i32 s58, s2, 31
	v_and_or_b32 v4, v0, s0, v4
	s_lshr_b32 s0, s58, 29
	s_add_i32 s0, s2, s0
	s_ashr_i32 s8, s1, 6
	s_ashr_i32 s6, s0, 3
	s_and_b32 s0, s0, -8
	s_ashr_i32 s10, s1, 8
	s_lshl_b32 s57, s8, 10
	s_sub_i32 s0, s2, s0
	s_cmp_lt_i32 s0, 0
	s_movk_i32 s59, 0x135
	s_cselect_b32 s7, s59, 0x134
	s_mul_i32 s0, s0, s7
	s_add_i32 s0, s0, s6
	s_mul_hi_i32 s6, s0, 0x3531dec1
	s_lshr_b32 s7, s6, 31
	s_ashr_i32 s6, s6, 7
	s_add_i32 s6, s6, s7
	s_lshl_b32 s7, s6, 3
	s_mulk_i32 s6, 0x268
	s_sub_i32 s6, s0, s6
	s_sext_i32_i16 s0, s6
	s_bfe_u32 s0, s0, 0x3001c
	s_add_i32 s9, s6, s0
	s_sext_i32_i16 s0, s9
	s_and_b32 s9, s9, 0xfff8
	s_sub_i32 s6, s6, s9
	s_sext_i32_i16 s6, s6
	v_lshrrev_b32_e32 v5, 2, v0
	v_lshlrev_b32_e32 v6, 1, v0
	v_and_b32_e32 v2, 0xc0, v2
	s_lshr_b32 s0, s0, 3
	s_add_i32 s68, s7, s6
	v_and_b32_e32 v5, 4, v5
	v_and_b32_e32 v6, 24, v6
	v_sub_u32_e32 v1, v1, v2
	s_ashr_i32 s69, s68, 31
	s_bfe_i64 s[12:13], s[0:1], 0x100000
	v_or3_b32 v4, v4, v5, v6
	v_lshlrev_b32_e32 v5, 5, v13
	v_ashrrev_i16_sdwa v1, v3, sext(v1) dst_sel:DWORD dst_unused:UNUSED_PAD src0_sel:DWORD src1_sel:BYTE_0
	s_lshl_b64 s[6:7], s[68:69], 21
	s_lshl_b64 s[12:13], s[12:13], 21
	v_and_b32_e32 v5, 32, v5
	v_bfe_i32 v14, v1, 0, 16
	s_add_u32 s28, s4, s12
	v_add_lshl_u32 v1, v5, v14, 1
	s_addc_u32 s29, s5, s13
	s_add_i32 s69, s57, 0
	v_lshl_add_u32 v132, v4, 13, v1
	s_add_i32 m0, s69, 0x10000
	v_lshl_add_u32 v134, v0, 13, v1
	global_load_lds_dwordx4 v132, s[28:29]
	s_add_i32 m0, s69, 0x12000
	s_add_u32 s12, s28, 0x100000
	global_load_lds_dwordx4 v128, s[28:29]
	s_addc_u32 s13, s29, 0
	s_add_i32 m0, s69, 0x14000
	v_mov_b32_e32 v133, 0
	global_load_lds_dwordx4 v132, s[12:13]
	s_add_i32 m0, s69, 0x16000
	s_add_u32 s70, s54, s6
	s_addc_u32 s71, s55, s7
	s_add_i32 s74, s69, 0x2000
	global_load_lds_dwordx4 v128, s[12:13]
	s_mov_b32 m0, s69
	s_add_u32 s6, s70, 0x100000
	global_load_lds_dwordx4 v134, s[70:71]
	s_mov_b32 m0, s74
	s_addc_u32 s7, s71, 0
	s_add_i32 s75, s69, 0x4000
	global_load_lds_dwordx4 v130, s[70:71]
	s_mov_b32 m0, s75
	s_add_i32 s76, s69, 0x6000
	global_load_lds_dwordx4 v134, s[6:7]
	s_mov_b32 m0, s76
	v_mov_b32_e32 v129, v133
	global_load_lds_dwordx4 v130, s[6:7]
	v_mov_b32_e32 v135, v133
	v_mov_b32_e32 v131, v133
	s_cmp_eq_u32 s10, 1
	s_mov_b32 s77, 0
	v_lshl_add_u64 v[6:7], s[28:29], 0, v[132:133]
	v_lshl_add_u64 v[4:5], s[28:29], 0, v[128:129]
	v_lshl_add_u64 v[0:1], s[70:71], 0, v[134:135]
	s_cselect_b64 s[6:7], -1, 0
	s_cmp_lg_u32 s10, 1
	v_lshl_add_u64 v[2:3], s[70:71], 0, v[130:131]
	s_cbranch_scc1 .LBB8_260
	s_barrier
